# both layers: partial 4th round of the w_in GEMM (24 units, now hgrn-q / context-NA column tiles by a group-local unit swap) runs on hgrn workgroups 192-215 after the grid barrier; hgrn stage 1 re-deal
# speedup vs baseline: 1.0120x; 1.0120x over previous
.LBB0_423:
	v_readlane_b32 s42, v254, 31
	s_andn2_b64 vcc, exec, s[4:5]
	v_readlane_b32 s43, v254, 32
	s_cbranch_vccnz .LBB0_871
	v_readlane_b32 s2, v252, 20
	v_readlane_b32 s3, v252, 21
	s_mov_b64 s[0:1], -1
	s_and_b64 vcc, exec, s[2:3]
	s_cbranch_vccz .LBB0_426
	v_readlane_b32 s1, v254, 14
	s_movk_i32 s0, 0x140
	s_nop 0
	v_writelane_b32 v252, s0, 22
	s_sub_i32 s0, s78, 0xd8
	s_cmp_lt_i32 s0, 0
	s_cbranch_scc1 .Lst1_prod
	s_mul_i32 s2, s1, 40
	s_add_i32 s2, s2, s0
	s_branch .Lst1_set
.Lst1_prod:
	s_mul_i32 s2, s1, 24
	s_add_i32 s2, s2, s0
	s_addk_i32 s2, 0x798

.LBB0_426:
	s_andn2_b64 vcc, exec, s[0:1]
	s_movk_i32 s1, 0x840
	s_cmpk_ge_i32 s78, 0xd8
	s_cselect_b32 s1, 0x780, s1
	s_cbranch_vccnz .LBB0_428
	v_readlane_b32 s0, v253, 39
	v_readlane_b32 s1, v254, 14
	s_mul_i32 s0, s1, s0
	s_add_i32 s2, s0, s78
	v_readlane_b32 s1, v252, 18

.LBB0_527:
	s_or_b64 exec, exec, s[0:1]
	v_writelane_b32 v255, s0, 40
	v_writelane_b32 v255, s1, 41
	v_writelane_b32 v255, s2, 42
	v_writelane_b32 v255, s3, 43
	v_writelane_b32 v255, s4, 44
	v_readlane_b32 s2, v254, 44
	s_nop 3
	s_mov_b32 s3, 0
	s_cmp_eq_u32 s2, 3
	s_cbranch_scc1 .Ll4acq_go_h
	s_movk_i32 s3, 0x100
	s_cmp_eq_u32 s2, 10
	s_cbranch_scc0 .Ll4acq_done_h
.Ll4acq_go_h:
	s_cmpk_lt_i32 s78, 0xc0
	s_cbranch_scc1 .Ll4acq_done_h
	v_readfirstlane_b32 s4, v191
	s_nop 3
	s_cmp_lt_u32 s4, 64
	s_cbranch_scc0 .Ll4acq_bar_h
	v_readlane_b32 s0, v254, 10
	v_readlane_b32 s1, v254, 11
	s_nop 3
	s_add_u32 s0, s0, 0x16b00
	s_addc_u32 s1, s1, 0
	s_add_u32 s0, s0, s3
	s_addc_u32 s1, s1, 0
	s_mov_b32 s3, 0
	s_mov_b64 vcc, exec
	s_mov_b32 exec_lo, 0
	s_brev_b32 exec_hi, 1

.Ll4acq_done_h:
	v_readlane_b32 s0, v255, 40
	v_readlane_b32 s1, v255, 41
	v_readlane_b32 s2, v255, 42
	v_readlane_b32 s3, v255, 43
	v_readlane_b32 s4, v255, 44
	s_nop 3
	v_readlane_b32 s0, v254, 14
	s_cmp_eq_u32 s0, 4
	v_readlane_b32 s2, v254, 33
	s_cselect_b64 s[0:1], -1, 0
	v_readlane_b32 s3, v254, 34
	s_and_b64 s[0:1], s[2:3], s[0:1]
	s_and_b64 vcc, exec, s[0:1]
	s_barrier
	s_cbranch_vccz .LBB0_587
	v_readlane_b32 s0, v252, 27
	v_readlane_b32 s1, v252, 28
	s_andn2_b64 vcc, exec, s[0:1]
	s_cbranch_vccnz .LBB0_587
	s_load_dwordx2 s[0:1], s[42:43], 0x40
	v_or_b32_e32 v2, s44, v223
	v_ashrrev_i32_e32 v3, 31, v2
	v_and_b32_e32 v4, 15, v188
	v_lshlrev_b32_e32 v0, 2, v223
	s_waitcnt lgkmcnt(0)
	v_lshl_add_u64 v[2:3], v[2:3], 2, s[0:1]
	global_load_dword v98, v[2:3], off
	v_lshlrev_b32_e32 v2, 4, v4
	v_readlane_b32 s0, v253, 45
	v_mov_b32_e32 v3, v1
	v_lshl_add_u64 v[6:7], s[36:37], 0, v[0:1]
	v_add_u32_e32 v5, s0, v2
	v_readlane_b32 s0, v254, 29
	v_readlane_b32 s1, v254, 30
	v_lshlrev_b32_e32 v0, 3, v4
	v_lshrrev_b32_e32 v99, 4, v223
	v_lshl_add_u64 v[8:9], s[0:1], 0, v[2:3]
	v_readlane_b32 s0, v254, 48
	v_readlane_b32 s1, v254, 49
	v_mul_i32_i24_e32 v20, -12, v4
	v_readlane_b32 s8, v252, 30
	v_lshl_add_u64 v[10:11], s[0:1], 0, v[0:1]
	v_readlane_b32 s0, v254, 46
	v_readlane_b32 s1, v254, 47
	v_cmp_eq_u32_e64 s[40:41], 2, v99
	v_lshl_add_u32 v106, v4, 1, 0
	v_lshl_add_u64 v[12:13], s[0:1], 0, v[0:1]
	v_lshlrev_b32_e32 v0, 8, v99
	v_readlane_b32 s1, v253, 47
	v_readlane_b32 s0, v253, 46
	v_add_u32_e32 v102, v5, v0
	v_add3_u32 v100, s1, v2, v0
	v_add3_u32 v101, s0, v2, v0
	v_lshlrev_b32_e32 v0, 2, v188
	v_and_b32_e32 v0, 0xc0, v0
	v_add_u32_e32 v103, s1, v0
	v_add_u32_e32 v104, s0, v0
	v_readlane_b32 s0, v254, 25
	v_readlane_b32 s1, v254, 26
	v_lshlrev_b32_e32 v0, 1, v223
	v_add_u32_e32 v105, 0, v0
	v_lshl_add_u64 v[14:15], s[0:1], 0, v[2:3]
	v_readlane_b32 s0, v254, 21
	v_readlane_b32 s1, v254, 22
	v_lshl_add_u64 v[18:19], s[54:55], 0, v[0:1]
	s_mov_b32 s6, s8
	v_lshl_add_u64 v[16:17], s[0:1], 0, v[0:1]
	v_add_u32_e32 v0, v5, v20
	v_readlane_b32 s7, v253, 37
	s_branch .LBB0_531

.LBB0_764:
	v_writelane_b32 v255, s0, 40
	v_writelane_b32 v255, s1, 41
	v_writelane_b32 v255, s2, 42
	v_writelane_b32 v255, s3, 43
	v_writelane_b32 v255, s4, 44
	v_readlane_b32 s2, v254, 44
	s_nop 3
	s_mov_b32 s3, 0
	s_cmp_eq_u32 s2, 3
	s_cbranch_scc1 .Ll4acq_go_n
	s_movk_i32 s3, 0x100
	s_cmp_eq_u32 s2, 10
	s_cbranch_scc0 .Ll4acq_done_n
.Ll4acq_go_n:
	v_readfirstlane_b32 s4, v191
	s_nop 3
	s_cmp_lt_u32 s4, 64
	s_cbranch_scc0 .Ll4acq_bar_n
	v_readlane_b32 s0, v254, 10
	v_readlane_b32 s1, v254, 11
	s_nop 3
	s_add_u32 s0, s0, 0x16b00
	s_addc_u32 s1, s1, 0
	s_add_u32 s0, s0, s3
	s_addc_u32 s1, s1, 0
	s_mov_b32 s3, 0
	s_mov_b64 vcc, exec
	s_mov_b32 exec_lo, 0
	s_brev_b32 exec_hi, 1

.LBB0_928:
	s_andn2_b64 vcc, exec, s[0:1]
	s_cbranch_vccnz .LBB0_1331
	v_readlane_b32 s0, v252, 41
	v_readlane_b32 s1, v252, 42
	v_mov_b32_e32 v0, v191
	s_andn2_b64 vcc, exec, s[0:1]
	v_cndmask_b32_e64 v2, 0, 1, s[0:1]
	v_cmp_ne_u32_e64 s[40:41], 1, v2
	v_readfirstlane_b32 s6, v0
	s_cbranch_vccnz .LBB0_931
	v_readlane_b32 s0, v253, 41
	s_mov_b32 s66, s0
	v_readlane_b32 s0, v253, 34
	v_readlane_b32 s3, v255, 61
	s_nop 3
	s_add_i32 s4, s78, 64
	s_and_b32 s4, s4, 0xff
	s_cmp_eq_u32 s3, 1
	s_cselect_b32 s3, 0x300, 0
	s_add_i32 s4, s4, s3
	s_and_b32 s5, s4, 7
	s_lshr_b32 s4, s4, 3
	s_mul_i32 s5, s5, 0x63
	s_add_i32 s4, s4, s5
	s_mul_hi_u32 s5, s4, 0x2aaaaaab
	s_lshr_b32 s5, s5, 4
	s_mul_i32 s3, s5, 0x60
	s_sub_i32 s4, s4, s3
	s_lshl_b32 s9, s5, 3
	s_cmp_lt_u32 s9, 64
	s_cselect_b32 s3, 3, 1
	s_lshr_b32 s66, s4, s3
	s_lshl_b32 s2, s66, s3
	s_sub_i32 s2, s4, s2
	s_add_i32 s0, s9, s2
	s_cmp_lt_u32 s9, 64
	s_cbranch_scc0 .Lperm_done_f
	s_cmp_eq_u32 s5, 0
	s_cbranch_scc1 .Lperm_done_f
	s_sub_i32 s2, s5, 1
	s_mul_i32 s2, s2, 3
	s_sub_i32 s3, s4, s2
	s_cmp_lt_u32 s4, 8
	s_cbranch_scc1 .Lperm_small_f
	s_cmp_lt_u32 s3, 3
	s_cselect_b32 s66, 0, s66
	s_branch .Lperm_done_f
.Lperm_small_f:
	s_add_i32 s3, s3, 8
	s_cmp_lt_u32 s3, 3
	s_cselect_b32 s66, 1, s66
	s_add_i32 s3, s3, 8
	s_cmp_lt_u32 s3, 3
	s_cselect_b32 s66, 2, s66

.LBB0_937:
	s_add_i32 s26, s26, 1
	v_readlane_b32 s1, v255, 61
	s_mul_i32 s6, s26, s80
	s_nop 2
	s_cmp_eq_u32 s1, 1
	s_cselect_b32 s1, 0x300, 0
	s_add_i32 s6, s6, s1
	s_add_i32 s1, s78, 64
	s_and_b32 s1, s1, 0xff
	s_add_i32 s6, s6, s1
	s_cmp_lt_u32 s6, 0x300
	s_cselect_b64 s[40:41], -1, 0
	s_cbranch_scc0 .LBB0_939
	s_ashr_i32 s1, s6, 31
	s_lshr_b32 s1, s1, 29
	s_add_i32 s1, s6, s1
	s_ashr_i32 s7, s1, 3
	s_and_b32 s1, s1, -8
	s_sub_i32 s1, s6, s1
	s_cmp_lt_i32 s1, 0
	s_cselect_b32 s6, s38, 0x63
	s_mul_i32 s1, s1, s6
	s_add_i32 s1, s1, s7
	s_mul_hi_i32 s6, s1, 0x2aaaaaab
	s_lshr_b32 s7, s6, 31
	s_ashr_i32 s6, s6, 4
	s_add_i32 s6, s6, s7
	s_lshl_b32 s7, s6, 3
	s_sub_i32 s12, 0x42, s7
	s_min_i32 s12, s12, 8
	s_abs_i32 s13, s12
	v_cvt_f32_u32_e32 v0, s13
	s_sub_i32 s28, 0, s13
	s_mulk_i32 s6, 0x60
	s_sub_i32 s1, s1, s6
	v_rcp_iflag_f32_e32 v0, v0
	s_abs_i32 s6, s1
	s_xor_b32 s27, s1, s12
	s_ashr_i32 s27, s27, 31
	v_mul_f32_e32 v0, 0x4f7ffffe, v0
	v_cvt_u32_f32_e32 v0, v0
	s_nop 0
	v_readfirstlane_b32 s29, v0
	s_mul_i32 s28, s28, s29
	s_mul_hi_u32 s28, s29, s28
	s_add_i32 s29, s29, s28
	s_mul_hi_u32 s28, s6, s29
	s_mul_i32 s29, s28, s13
	s_sub_i32 s6, s6, s29
	s_add_i32 s30, s28, 1
	s_sub_i32 s29, s6, s13
	s_cmp_ge_u32 s6, s13
	s_cselect_b32 s28, s30, s28
	s_cselect_b32 s6, s29, s6
	s_add_i32 s29, s28, 1
	s_cmp_ge_u32 s6, s13
	s_cselect_b32 s6, s29, s28
	s_xor_b32 s6, s6, s27
	s_sub_i32 s58, s6, s27
	s_mul_i32 s6, s58, s12
	s_sub_i32 s1, s1, s6
	s_add_i32 s60, s7, s1
	s_mul_i32 s6, s58, s12
	s_add_i32 s6, s6, s1
	s_lshr_b32 s27, s7, 3
	s_cmp_lt_u32 s7, 64
	s_cbranch_scc0 .Lperm_done_n
	s_cmp_eq_u32 s27, 0
	s_cbranch_scc1 .Lperm_done_n
	s_sub_i32 s28, s27, 1
	s_mul_i32 s28, s28, 3
	s_sub_i32 s29, s6, s28
	s_cmp_lt_u32 s6, 8
	s_cbranch_scc1 .Lperm_small_n
	s_cmp_lt_u32 s29, 3
	s_cselect_b32 s58, 0, s58
	s_branch .Lperm_done_n
.Lperm_small_n:
	s_add_i32 s29, s29, 8
	s_cmp_lt_u32 s29, 3
	s_cselect_b32 s58, 1, s58
	s_add_i32 s29, s29, 8
	s_cmp_lt_u32 s29, 3
	s_cselect_b32 s58, 2, s58
.Lperm_done_n:
.LBB0_939:
	s_ashr_i32 s61, s60, 31
	s_lshl_b64 s[6:7], s[60:61], 19
	s_add_u32 s62, s44, s6
	s_addc_u32 s63, s45, s7
	s_and_b64 s[6:7], s[40:41], exec
	s_cselect_b32 s1, s63, s3
	s_cselect_b32 s12, s62, s2
	s_ashr_i32 s59, s58, 31
	s_lshl_b64 s[6:7], s[58:59], 19
	s_add_u32 s64, s8, s6
	s_addc_u32 s65, s9, s7
	s_and_b64 s[6:7], s[40:41], exec
	s_cselect_b32 s13, s65, s5
	s_cselect_b32 s27, s64, s4
	s_add_u32 s2, s2, 0x40080
	s_addc_u32 s3, s3, 0
	s_add_u32 s28, s4, 0x100
	v_mov_b32_e32 v2, 0
	s_addc_u32 s29, s5, 0
	s_mov_b32 s30, -2
	v_mov_b32_e32 v3, v2
	v_mov_b32_e32 v4, v2
	v_mov_b32_e32 v5, v2
	v_mov_b32_e32 v6, v2
	v_mov_b32_e32 v7, v2
	v_mov_b32_e32 v8, v2
	v_mov_b32_e32 v9, v2
	v_mov_b32_e32 v18, v2
	v_mov_b32_e32 v19, v2
	v_mov_b32_e32 v20, v2
	v_mov_b32_e32 v21, v2
	v_mov_b32_e32 v22, v2
	v_mov_b32_e32 v23, v2
	v_mov_b32_e32 v24, v2
	v_mov_b32_e32 v25, v2
	v_mov_b32_e32 v34, v2
	v_mov_b32_e32 v35, v2
	v_mov_b32_e32 v36, v2
	v_mov_b32_e32 v37, v2
	v_mov_b32_e32 v38, v2
	v_mov_b32_e32 v39, v2
	v_mov_b32_e32 v40, v2
	v_mov_b32_e32 v41, v2
	v_mov_b32_e32 v50, v2
	v_mov_b32_e32 v51, v2
	v_mov_b32_e32 v52, v2
	v_mov_b32_e32 v53, v2
	v_mov_b32_e32 v54, v2
	v_mov_b32_e32 v55, v2
	v_mov_b32_e32 v56, v2
	v_mov_b32_e32 v57, v2
	v_mov_b32_e32 v10, v2
	v_mov_b32_e32 v11, v2
	v_mov_b32_e32 v12, v2
	v_mov_b32_e32 v13, v2
	v_mov_b32_e32 v14, v2
	v_mov_b32_e32 v15, v2
	v_mov_b32_e32 v16, v2
	v_mov_b32_e32 v17, v2
	v_mov_b32_e32 v26, v2
	v_mov_b32_e32 v27, v2
	v_mov_b32_e32 v28, v2
	v_mov_b32_e32 v29, v2
	v_mov_b32_e32 v30, v2
	v_mov_b32_e32 v31, v2
	v_mov_b32_e32 v32, v2
	v_mov_b32_e32 v33, v2
	v_mov_b32_e32 v42, v2
	v_mov_b32_e32 v43, v2
	v_mov_b32_e32 v44, v2
	v_mov_b32_e32 v45, v2
	v_mov_b32_e32 v46, v2
	v_mov_b32_e32 v47, v2
	v_mov_b32_e32 v48, v2
	v_mov_b32_e32 v49, v2
	v_mov_b32_e32 v58, v2
	v_mov_b32_e32 v59, v2
	v_mov_b32_e32 v60, v2
	v_mov_b32_e32 v61, v2
	v_mov_b32_e32 v62, v2
	v_mov_b32_e32 v63, v2
	v_mov_b32_e32 v64, v2
	v_mov_b32_e32 v65, v2
	v_mov_b32_e32 v66, v2
	v_mov_b32_e32 v67, v2
	v_mov_b32_e32 v68, v2
	v_mov_b32_e32 v69, v2
	v_mov_b32_e32 v70, v2
	v_mov_b32_e32 v71, v2
	v_mov_b32_e32 v72, v2
	v_mov_b32_e32 v73, v2
	v_mov_b32_e32 v82, v2
	v_mov_b32_e32 v83, v2
	v_mov_b32_e32 v84, v2
	v_mov_b32_e32 v85, v2
	v_mov_b32_e32 v86, v2
	v_mov_b32_e32 v87, v2
	v_mov_b32_e32 v88, v2
	v_mov_b32_e32 v89, v2
	v_mov_b32_e32 v98, v2
	v_mov_b32_e32 v99, v2
	v_mov_b32_e32 v100, v2
	v_mov_b32_e32 v101, v2
	v_mov_b32_e32 v102, v2
	v_mov_b32_e32 v103, v2
	v_mov_b32_e32 v104, v2
	v_mov_b32_e32 v105, v2
	v_mov_b32_e32 v114, v2
	v_mov_b32_e32 v115, v2
	v_mov_b32_e32 v116, v2
	v_mov_b32_e32 v117, v2
	v_mov_b32_e32 v118, v2
	v_mov_b32_e32 v119, v2
	v_mov_b32_e32 v120, v2
	v_mov_b32_e32 v121, v2
	v_mov_b32_e32 v74, v2
	v_mov_b32_e32 v75, v2
	v_mov_b32_e32 v76, v2
	v_mov_b32_e32 v77, v2
	v_mov_b32_e32 v78, v2
	v_mov_b32_e32 v79, v2
	v_mov_b32_e32 v80, v2
	v_mov_b32_e32 v81, v2
	v_mov_b32_e32 v90, v2
	v_mov_b32_e32 v91, v2
	v_mov_b32_e32 v92, v2
	v_mov_b32_e32 v93, v2
	v_mov_b32_e32 v94, v2
	v_mov_b32_e32 v95, v2
	v_mov_b32_e32 v96, v2
	v_mov_b32_e32 v97, v2
	v_mov_b32_e32 v106, v2
	v_mov_b32_e32 v107, v2
	v_mov_b32_e32 v108, v2
	v_mov_b32_e32 v109, v2
	v_mov_b32_e32 v110, v2
	v_mov_b32_e32 v111, v2
	v_mov_b32_e32 v112, v2
	v_mov_b32_e32 v113, v2
	v_mov_b32_e32 v122, v2
	v_mov_b32_e32 v123, v2
	v_mov_b32_e32 v124, v2
	v_mov_b32_e32 v125, v2
	v_mov_b32_e32 v126, v2
	v_mov_b32_e32 v127, v2
	v_mov_b32_e32 v128, v2
	v_mov_b32_e32 v129, v2
	s_mov_b64 s[36:37], 0x80

.LBB0_1378:
	v_readlane_b32 s0, v255, 61
	s_nop 3
	s_cmp_eq_u32 s0, 1
	s_cbranch_scc0 .Ll4_a
	s_waitcnt vmcnt(0)
	s_barrier
	s_mov_b32 s0, 0
	v_writelane_b32 v255, s0, 61
	v_readfirstlane_b32 s0, v191
	s_nop 3
	s_cmp_ge_u32 s0, 64
	s_cbranch_scc1 .Ll4_nopub
	v_readlane_b32 s0, v254, 10
	v_readlane_b32 s1, v254, 11
	s_nop 3
	s_add_u32 s0, s0, 0x16b00
	s_addc_u32 s1, s1, 0
	s_cmp_eq_u32 s54, 9
	s_cselect_b32 vcc_lo, 0x100, 0
	s_add_u32 s0, s0, vcc_lo
	s_addc_u32 s1, s1, 0
	s_mov_b64 vcc, exec
	s_mov_b64 exec, 1
	buffer_wbl2 sc1
	s_waitcnt vmcnt(0)
	global_atomic_add v1, v220, s[0:1]
	s_mov_b64 exec, vcc

.Ll4_a:
	s_cmp_eq_u32 s54, 2
	s_cbranch_scc1 .Ll4_pb
	s_cmp_eq_u32 s54, 9
	s_cbranch_scc0 .Ll4_b
.Ll4_pb:
	s_sub_i32 s0, s78, 0xc0
	s_cmp_lt_u32 s0, 24
	s_cbranch_scc0 .Ll4_b
	s_mov_b32 s0, 1
	v_writelane_b32 v255, s0, 61
	s_sub_i32 s54, s54, 1
